# attn gather prefetch distance 2 (two register sets), on top of v30
# baseline (speedup 1.0000x reference)
.LBB0_1399:
	s_waitcnt lgkmcnt(0)
	s_barrier
	v_add_u32_e32 v67, 0xc000, v71
	ds_read_b64_tr_b16 v[12:13], v81 offset:8448
	ds_read_b64_tr_b16 v[10:11], v80 offset:58880
	ds_read2_b64 v[14:17], v67 offset0:80 offset1:82
	ds_read_b64_tr_b16 v[20:21], v81 offset:8480
	ds_read_b64_tr_b16 v[18:19], v80 offset:58912
	ds_read_b64_tr_b16 v[22:23], v80 offset:58944
	ds_read_b64_tr_b16 v[42:43], v80 offset:58976
	ds_read_b64_tr_b16 v[24:25], v81 offset:8512
	ds_read_b64_tr_b16 v[44:45], v81 offset:8544
	s_waitcnt lgkmcnt(6)
	v_mfma_f32_16x16x32_bf16 v[10:13], v[10:13], v[14:17], 0
	ds_read_b64_tr_b16 v[48:49], v88 offset:8448
	ds_read_b64_tr_b16 v[46:47], v88
	s_andn2_b64 vcc, exec, s[10:11]
	s_waitcnt lgkmcnt(6)
	v_mfma_f32_16x16x32_bf16 v[18:21], v[18:21], v[14:17], 0
	s_waitcnt lgkmcnt(3)
	v_mfma_f32_16x16x32_bf16 v[22:25], v[22:25], v[14:17], 0
	s_waitcnt lgkmcnt(2)
	v_mfma_f32_16x16x32_bf16 v[14:17], v[42:45], v[14:17], 0
	ds_read2_b64 v[42:45], v67 offset0:88 offset1:90
	ds_read_b64_tr_b16 v[50:51], v88 offset:32
	ds_read_b64_tr_b16 v[54:55], v88 offset:64
	ds_read_b64_tr_b16 v[92:93], v88 offset:96
	ds_read_b64_tr_b16 v[52:53], v88 offset:8480
	ds_read_b64_tr_b16 v[56:57], v88 offset:8512
	ds_read_b64_tr_b16 v[94:95], v88 offset:8544
	s_waitcnt lgkmcnt(0)
	s_barrier
	s_waitcnt vmcnt(11)
	ds_write_b128 v82, v[152:155]
	s_waitcnt vmcnt(10)
	ds_write_b128 v82, v[156:159] offset:8448
	s_waitcnt vmcnt(9)
	ds_write_b128 v82, v[160:163] offset:16896
	s_waitcnt vmcnt(8)
	ds_write_b128 v82, v[164:167] offset:25344
	v_mov_b32_e32 v26, s16
	v_add_u32_e32 v112, 0xe000, v26
	ds_read2_b32 v[224:225], v90 offset0:128 offset1:136
	ds_read2_b32 v[226:227], v90 offset0:144 offset1:152
	ds_read2_b32 v[228:229], v90 offset0:160 offset1:168
	ds_read2_b32 v[230:231], v90 offset0:176 offset1:184
	v_mov_b32_e32 v241, 0
	s_waitcnt lgkmcnt(3)
	v_max_i32_e32 v240, 0, v224
	v_lshlrev_b64 v[242:243], 10, v[240:241]
	v_lshl_add_u64 v[242:243], v[62:63], 0, v[242:243]
	global_load_dwordx4 v[152:155], v[242:243], off
	v_max_i32_e32 v240, 0, v225
	v_lshlrev_b64 v[244:245], 10, v[240:241]
	v_lshl_add_u64 v[244:245], v[62:63], 0, v[244:245]
	global_load_dwordx4 v[156:159], v[244:245], off
	s_waitcnt lgkmcnt(2)
	v_max_i32_e32 v240, 0, v226
	v_lshlrev_b64 v[246:247], 10, v[240:241]
	v_lshl_add_u64 v[246:247], v[62:63], 0, v[246:247]
	global_load_dwordx4 v[160:163], v[246:247], off
	v_max_i32_e32 v240, 0, v227
	v_lshlrev_b64 v[248:249], 10, v[240:241]
	v_lshl_add_u64 v[248:249], v[62:63], 0, v[248:249]
	global_load_dwordx4 v[164:167], v[248:249], off
	s_waitcnt lgkmcnt(1)
	v_max_i32_e32 v240, 0, v228
	v_lshlrev_b64 v[242:243], 10, v[240:241]
	v_lshl_add_u64 v[242:243], v[62:63], 0, v[242:243]
	global_load_dwordx4 v[168:171], v[242:243], off
	v_max_i32_e32 v240, 0, v229
	v_lshlrev_b64 v[244:245], 10, v[240:241]
	v_lshl_add_u64 v[244:245], v[62:63], 0, v[244:245]
	global_load_dwordx4 v[172:175], v[244:245], off
	s_waitcnt lgkmcnt(0)
	v_max_i32_e32 v240, 0, v230
	v_lshlrev_b64 v[246:247], 10, v[240:241]
	v_lshl_add_u64 v[246:247], v[62:63], 0, v[246:247]
	global_load_dwordx4 v[176:179], v[246:247], off
	v_max_i32_e32 v240, 0, v231
	v_lshlrev_b64 v[248:249], 10, v[240:241]
	v_lshl_add_u64 v[248:249], v[62:63], 0, v[248:249]
	global_load_dwordx4 v[180:183], v[248:249], off
	s_waitcnt lgkmcnt(12)
	v_mfma_f32_16x16x32_bf16 v[10:13], v[46:49], v[42:45], v[10:13]
	s_waitcnt lgkmcnt(1)
	s_waitcnt lgkmcnt(0)
	v_mfma_f32_16x16x32_bf16 v[18:21], v[50:53], v[42:45], v[18:21]
	s_waitcnt lgkmcnt(1)
	s_waitcnt lgkmcnt(0)
	s_waitcnt lgkmcnt(0)
	s_barrier
	v_mfma_f32_16x16x32_bf16 v[22:25], v[54:57], v[42:45], v[22:25]
	ds_read_b64_tr_b16 v[56:57], v81 offset:8448
	ds_read_b64_tr_b16 v[54:55], v80 offset:58880
	v_mfma_f32_16x16x32_bf16 v[14:17], v[92:95], v[42:45], v[14:17]
	ds_read2_b64 v[42:45], v67 offset0:64 offset1:66
	ds_read_b64_tr_b16 v[94:95], v81 offset:8480
	ds_read_b64_tr_b16 v[92:93], v80 offset:58912
	ds_read_b64_tr_b16 v[104:105], v80 offset:58944
	ds_read_b64_tr_b16 v[108:109], v80 offset:58976
	ds_read_b64_tr_b16 v[106:107], v81 offset:8512
	ds_read_b64_tr_b16 v[110:111], v81 offset:8544
	s_waitcnt lgkmcnt(6)
	v_mfma_f32_16x16x32_bf16 v[10:13], v[54:57], v[42:45], v[10:13]
	ds_read_b64_tr_b16 v[56:57], v89 offset:8448
	ds_read_b64_tr_b16 v[54:55], v89
	s_waitcnt lgkmcnt(6)
	v_mfma_f32_16x16x32_bf16 v[18:21], v[92:95], v[42:45], v[18:21]
	s_waitcnt lgkmcnt(3)
	v_mfma_f32_16x16x32_bf16 v[22:25], v[104:107], v[42:45], v[22:25]
	s_waitcnt lgkmcnt(2)
	v_mfma_f32_16x16x32_bf16 v[14:17], v[108:111], v[42:45], v[14:17]
	ds_read2_b64 v[42:45], v67 offset0:72 offset1:74
	ds_read_b64_tr_b16 v[92:93], v89 offset:32
	ds_read_b64_tr_b16 v[104:105], v89 offset:64
	ds_read_b64_tr_b16 v[108:109], v89 offset:96
	ds_read_b64_tr_b16 v[94:95], v89 offset:8480
	ds_read_b64_tr_b16 v[106:107], v89 offset:8512
	ds_read_b64_tr_b16 v[110:111], v89 offset:8544
	s_waitcnt lgkmcnt(0)
	s_barrier
	s_waitcnt lgkmcnt(6)
	v_mfma_f32_16x16x32_bf16 v[10:13], v[54:57], v[42:45], v[10:13]
	s_waitcnt vmcnt(15)
	ds_write_b128 v82, v[184:187]
	s_waitcnt vmcnt(14)
	ds_write_b128 v82, v[188:191] offset:8448
	s_waitcnt vmcnt(13)
	ds_write_b128 v82, v[192:195] offset:16896
	s_waitcnt vmcnt(12)
	ds_write_b128 v82, v[196:199] offset:25344
	s_waitcnt vmcnt(11)
	ds_write_b128 v82, v[200:203] offset:33792
	s_waitcnt vmcnt(10)
	ds_write_b128 v82, v[204:207] offset:42240
	s_waitcnt vmcnt(9)
	ds_write_b128 v82, v[208:211] offset:50688
	s_waitcnt vmcnt(8)
	ds_write_b128 v82, v[212:215] offset:59136
	s_waitcnt lgkmcnt(12)
	v_mfma_f32_16x16x32_bf16 v[18:21], v[92:95], v[42:45], v[18:21]
	s_waitcnt lgkmcnt(1)
	s_waitcnt lgkmcnt(0)
	s_waitcnt lgkmcnt(1)
	s_waitcnt lgkmcnt(0)
	s_waitcnt lgkmcnt(0)
	s_barrier
	ds_read_b64_tr_b16 v[98:99], v81 offset:8448
	ds_read_b64_tr_b16 v[96:97], v80 offset:58880
	v_mfma_f32_16x16x32_bf16 v[22:25], v[104:107], v[42:45], v[22:25]
	v_mfma_f32_16x16x32_bf16 v[14:17], v[108:111], v[42:45], v[14:17]
	ds_read2_b64 v[42:45], v67 offset0:48 offset1:50
	ds_read_b64_tr_b16 v[102:103], v81 offset:8480
	ds_read_b64_tr_b16 v[100:101], v80 offset:58912
	ds_read_b64_tr_b16 v[104:105], v80 offset:58944
	ds_read_b64_tr_b16 v[108:109], v80 offset:58976
	ds_read_b64_tr_b16 v[106:107], v81 offset:8512
	ds_read_b64_tr_b16 v[110:111], v81 offset:8544
	s_waitcnt lgkmcnt(6)
	v_mfma_f32_16x16x32_bf16 v[10:13], v[96:99], v[42:45], v[10:13]
	ds_read_b64_tr_b16 v[98:99], v88 offset:8448
	s_waitcnt lgkmcnt(5)
	v_mfma_f32_16x16x32_bf16 v[18:21], v[100:103], v[42:45], v[18:21]
	s_waitcnt lgkmcnt(2)
	v_mfma_f32_16x16x32_bf16 v[22:25], v[104:107], v[42:45], v[22:25]
	ds_read_b64_tr_b16 v[96:97], v88
	ds_read2_b64 v[100:103], v67 offset0:56 offset1:58
	ds_read_b64_tr_b16 v[106:107], v88 offset:8480
	s_waitcnt lgkmcnt(4)
	v_mfma_f32_16x16x32_bf16 v[14:17], v[108:111], v[42:45], v[14:17]
	ds_read_b64_tr_b16 v[104:105], v88 offset:32
	ds_read_b64_tr_b16 v[42:43], v88 offset:64
	ds_read_b64_tr_b16 v[108:109], v88 offset:96
	ds_read_b64_tr_b16 v[44:45], v88 offset:8512
	ds_read_b64_tr_b16 v[110:111], v88 offset:8544
	s_waitcnt lgkmcnt(0)
	s_barrier
	s_waitcnt vmcnt(7)
	ds_write_b128 v82, v[152:155]
	s_waitcnt vmcnt(6)
	ds_write_b128 v82, v[156:159] offset:8448
	s_waitcnt vmcnt(5)
	ds_write_b128 v82, v[160:163] offset:16896
	s_waitcnt vmcnt(4)
	ds_write_b128 v82, v[164:167] offset:25344
	s_waitcnt vmcnt(3)
	ds_write_b128 v82, v[168:171] offset:33792
	s_waitcnt vmcnt(2)
	ds_write_b128 v82, v[172:175] offset:42240
	s_waitcnt vmcnt(1)
	ds_write_b128 v82, v[176:179] offset:50688
	s_waitcnt vmcnt(0)
	ds_write_b128 v82, v[180:183] offset:59136
	s_waitcnt lgkmcnt(0)
	s_barrier
	ds_read_b64_tr_b16 v[28:29], v81 offset:8448
	ds_read_b64_tr_b16 v[26:27], v80 offset:58880
	s_waitcnt lgkmcnt(14)
	v_mfma_f32_16x16x32_bf16 v[10:13], v[96:99], v[100:103], v[10:13]
	v_mfma_f32_16x16x32_bf16 v[18:21], v[104:107], v[100:103], v[18:21]
	s_waitcnt lgkmcnt(11)
	v_mfma_f32_16x16x32_bf16 v[22:25], v[42:45], v[100:103], v[22:25]
	ds_read2_b64 v[30:33], v67 offset0:32 offset1:34
	ds_read_b64_tr_b16 v[36:37], v81 offset:8480
	ds_read_b64_tr_b16 v[34:35], v80 offset:58912
	ds_read_b64_tr_b16 v[38:39], v80 offset:58944
	ds_read_b64_tr_b16 v[42:43], v80 offset:58976
	ds_read_b64_tr_b16 v[40:41], v81 offset:8512
	ds_read_b64_tr_b16 v[44:45], v81 offset:8544
	s_waitcnt lgkmcnt(14)
	v_mfma_f32_16x16x32_bf16 v[14:17], v[108:111], v[100:103], v[14:17]
	s_waitcnt lgkmcnt(6)
	v_mfma_f32_16x16x32_bf16 v[10:13], v[26:29], v[30:33], v[10:13]
	ds_read_b64_tr_b16 v[28:29], v88 offset:8448
	ds_read_b64_tr_b16 v[26:27], v88
	s_waitcnt lgkmcnt(6)
	v_mfma_f32_16x16x32_bf16 v[18:21], v[34:37], v[30:33], v[18:21]
	s_waitcnt lgkmcnt(3)
	v_mfma_f32_16x16x32_bf16 v[22:25], v[38:41], v[30:33], v[22:25]
	s_waitcnt lgkmcnt(2)
	v_mfma_f32_16x16x32_bf16 v[14:17], v[42:45], v[30:33], v[14:17]
	ds_read2_b64 v[30:33], v67 offset0:40 offset1:42
	ds_read_b64_tr_b16 v[36:37], v88 offset:8480
	ds_read_b64_tr_b16 v[34:35], v88 offset:32
	ds_read_b64_tr_b16 v[38:39], v88 offset:64
	ds_read_b64_tr_b16 v[42:43], v88 offset:96
	ds_read_b64_tr_b16 v[40:41], v88 offset:8512
	ds_read_b64_tr_b16 v[44:45], v88 offset:8544
	s_waitcnt lgkmcnt(6)
	v_mfma_f32_16x16x32_bf16 v[10:13], v[26:29], v[30:33], v[10:13]
	s_waitcnt lgkmcnt(4)
	v_mfma_f32_16x16x32_bf16 v[18:21], v[34:37], v[30:33], v[18:21]
	s_waitcnt lgkmcnt(1)
	v_mfma_f32_16x16x32_bf16 v[22:25], v[38:41], v[30:33], v[22:25]
	s_nop 3
	v_cvt_pk_bf16_f32 v10, v10, v11
	v_cvt_pk_bf16_f32 v11, v12, v13
	global_store_dwordx2 v[64:65], v[10:11], off offset:-64
	s_waitcnt lgkmcnt(0)
	v_mfma_f32_16x16x32_bf16 v[14:17], v[42:45], v[30:33], v[14:17]
	v_cvt_pk_bf16_f32 v10, v18, v19
	v_cvt_pk_bf16_f32 v11, v20, v21
	global_store_dwordx2 v[64:65], v[10:11], off offset:-32
	v_cvt_pk_bf16_f32 v10, v22, v23
	v_cvt_pk_bf16_f32 v11, v24, v25
	global_store_dwordx2 v[64:65], v[10:11], off
	s_nop 1
	v_cvt_pk_bf16_f32 v10, v14, v15
	v_cvt_pk_bf16_f32 v11, v16, v17
	global_store_dwordx2 v[64:65], v[10:11], off offset:32
	v_lshl_add_u64 v[64:65], v[64:65], 0, s[0:1]
	s_cbranch_vccz .LBB0_1405
.LBB0_1400:
	s_waitcnt lgkmcnt(0)
	s_barrier
	s_waitcnt vmcnt(1)
	ds_write_b128 v68, v[2:5]
	s_waitcnt vmcnt(0)
	ds_write_b128 v69, v[6:9]
	s_and_saveexec_b64 s[10:11], s[4:5]
	ds_write_b32 v70, v1 offset:57856
	s_or_b64 exec, exec, s[10:11]
	s_waitcnt lgkmcnt(0)
	s_barrier
	ds_read2_b32 v[224:225], v90 offset0:128 offset1:136
	ds_read2_b32 v[226:227], v90 offset0:144 offset1:152
	ds_read2_b32 v[228:229], v90 offset0:160 offset1:168
	ds_read2_b32 v[230:231], v90 offset0:176 offset1:184
	ds_read2_b32 v[232:233], v90 offset0:192 offset1:200
	ds_read2_b32 v[234:235], v90 offset0:208 offset1:216
	ds_read2_b32 v[236:237], v90 offset0:224 offset1:232
	ds_read2_b32 v[238:239], v90 offset0:240 offset1:248
	v_mov_b32_e32 v241, 0
	s_waitcnt lgkmcnt(7)
	v_max_i32_e32 v240, 0, v224
	v_lshlrev_b64 v[242:243], 10, v[240:241]
	v_lshl_add_u64 v[242:243], v[62:63], 0, v[242:243]
	global_load_dwordx4 v[152:155], v[242:243], off
	v_max_i32_e32 v240, 0, v225
	v_lshlrev_b64 v[244:245], 10, v[240:241]
	v_lshl_add_u64 v[244:245], v[62:63], 0, v[244:245]
	global_load_dwordx4 v[156:159], v[244:245], off
	s_waitcnt lgkmcnt(6)
	v_max_i32_e32 v240, 0, v226
	v_lshlrev_b64 v[246:247], 10, v[240:241]
	v_lshl_add_u64 v[246:247], v[62:63], 0, v[246:247]
	global_load_dwordx4 v[160:163], v[246:247], off
	v_max_i32_e32 v240, 0, v227
	v_lshlrev_b64 v[248:249], 10, v[240:241]
	v_lshl_add_u64 v[248:249], v[62:63], 0, v[248:249]
	global_load_dwordx4 v[164:167], v[248:249], off
	s_waitcnt lgkmcnt(5)
	v_max_i32_e32 v240, 0, v228
	v_lshlrev_b64 v[242:243], 10, v[240:241]
	v_lshl_add_u64 v[242:243], v[62:63], 0, v[242:243]
	global_load_dwordx4 v[168:171], v[242:243], off
	v_max_i32_e32 v240, 0, v229
	v_lshlrev_b64 v[244:245], 10, v[240:241]
	v_lshl_add_u64 v[244:245], v[62:63], 0, v[244:245]
	global_load_dwordx4 v[172:175], v[244:245], off
	s_waitcnt lgkmcnt(4)
	v_max_i32_e32 v240, 0, v230
	v_lshlrev_b64 v[246:247], 10, v[240:241]
	v_lshl_add_u64 v[246:247], v[62:63], 0, v[246:247]
	global_load_dwordx4 v[176:179], v[246:247], off
	v_max_i32_e32 v240, 0, v231
	v_lshlrev_b64 v[248:249], 10, v[240:241]
	v_lshl_add_u64 v[248:249], v[62:63], 0, v[248:249]
	global_load_dwordx4 v[180:183], v[248:249], off
	s_waitcnt lgkmcnt(3)
	v_max_i32_e32 v240, 0, v232
	v_lshlrev_b64 v[242:243], 10, v[240:241]
	v_lshl_add_u64 v[242:243], v[62:63], 0, v[242:243]
	global_load_dwordx4 v[184:187], v[242:243], off
	v_max_i32_e32 v240, 0, v233
	v_lshlrev_b64 v[244:245], 10, v[240:241]
	v_lshl_add_u64 v[244:245], v[62:63], 0, v[244:245]
	global_load_dwordx4 v[188:191], v[244:245], off
	s_waitcnt lgkmcnt(2)
	v_max_i32_e32 v240, 0, v234
	v_lshlrev_b64 v[246:247], 10, v[240:241]
	v_lshl_add_u64 v[246:247], v[62:63], 0, v[246:247]
	global_load_dwordx4 v[192:195], v[246:247], off
	v_max_i32_e32 v240, 0, v235
	v_lshlrev_b64 v[248:249], 10, v[240:241]
	v_lshl_add_u64 v[248:249], v[62:63], 0, v[248:249]
	global_load_dwordx4 v[196:199], v[248:249], off
	s_waitcnt lgkmcnt(1)
	v_max_i32_e32 v240, 0, v236
	v_lshlrev_b64 v[242:243], 10, v[240:241]
	v_lshl_add_u64 v[242:243], v[62:63], 0, v[242:243]
	global_load_dwordx4 v[200:203], v[242:243], off
	v_max_i32_e32 v240, 0, v237
	v_lshlrev_b64 v[244:245], 10, v[240:241]
	v_lshl_add_u64 v[244:245], v[62:63], 0, v[244:245]
	global_load_dwordx4 v[204:207], v[244:245], off
	s_waitcnt lgkmcnt(0)
	v_max_i32_e32 v240, 0, v238
	v_lshlrev_b64 v[246:247], 10, v[240:241]
	v_lshl_add_u64 v[246:247], v[62:63], 0, v[246:247]
	global_load_dwordx4 v[208:211], v[246:247], off
	v_max_i32_e32 v240, 0, v239
	v_lshlrev_b64 v[248:249], 10, v[240:241]
	v_lshl_add_u64 v[248:249], v[62:63], 0, v[248:249]
	global_load_dwordx4 v[212:215], v[248:249], off
	s_add_i32 s6, s6, s8
	s_cmp_ge_i32 s6, s3
	s_waitcnt lgkmcnt(1)
	s_waitcnt lgkmcnt(0)
	s_waitcnt lgkmcnt(0)
	s_waitcnt lgkmcnt(0)
	ds_read_b128 v[54:57], v83
	ds_read_b128 v[46:49], v83 offset:64
	ds_read_b128 v[50:53], v83 offset:128
	ds_read_b128 v[42:45], v83 offset:192
	ds_read_b128 v[22:25], v83 offset:256
	ds_read_b128 v[18:21], v83 offset:320
	ds_read_b128 v[14:17], v83 offset:384
	ds_read_b128 v[10:13], v83 offset:448
	s_waitcnt lgkmcnt(0)
	s_barrier
	s_waitcnt vmcnt(15)
	ds_write_b128 v73, v[152:155] offset:58880
	s_waitcnt vmcnt(14)
	ds_write_b128 v74, v[156:159] offset:8448
	s_waitcnt vmcnt(13)
	ds_write_b128 v74, v[160:163] offset:16896
	s_waitcnt vmcnt(12)
	ds_write_b128 v74, v[164:167] offset:25344
	s_waitcnt vmcnt(11)
	ds_write_b128 v74, v[168:171] offset:33792
	s_waitcnt vmcnt(10)
	ds_write_b128 v74, v[172:175] offset:42240
	s_waitcnt vmcnt(9)
	ds_write_b128 v74, v[176:179] offset:50688
	s_waitcnt vmcnt(8)
	ds_write_b128 v74, v[180:183] offset:59136
	ds_read2_b32 v[224:225], v91 offset0:0 offset1:8
	ds_read2_b32 v[226:227], v91 offset0:16 offset1:24
	ds_read2_b32 v[228:229], v91 offset0:32 offset1:40
	ds_read2_b32 v[230:231], v91 offset0:48 offset1:56
	v_mov_b32_e32 v241, 0
	s_waitcnt lgkmcnt(3)
	v_max_i32_e32 v240, 0, v224
	v_lshlrev_b64 v[242:243], 10, v[240:241]
	v_lshl_add_u64 v[242:243], v[62:63], 0, v[242:243]
	global_load_dwordx4 v[152:155], v[242:243], off
	v_max_i32_e32 v240, 0, v225
	v_lshlrev_b64 v[244:245], 10, v[240:241]
	v_lshl_add_u64 v[244:245], v[62:63], 0, v[244:245]
	global_load_dwordx4 v[156:159], v[244:245], off
	s_waitcnt lgkmcnt(2)
	v_max_i32_e32 v240, 0, v226
	v_lshlrev_b64 v[246:247], 10, v[240:241]
	v_lshl_add_u64 v[246:247], v[62:63], 0, v[246:247]
	global_load_dwordx4 v[160:163], v[246:247], off
	v_max_i32_e32 v240, 0, v227
	v_lshlrev_b64 v[248:249], 10, v[240:241]
	v_lshl_add_u64 v[248:249], v[62:63], 0, v[248:249]
	global_load_dwordx4 v[164:167], v[248:249], off
	s_waitcnt lgkmcnt(1)
	v_max_i32_e32 v240, 0, v228
	v_lshlrev_b64 v[242:243], 10, v[240:241]
	v_lshl_add_u64 v[242:243], v[62:63], 0, v[242:243]
	global_load_dwordx4 v[168:171], v[242:243], off
	v_max_i32_e32 v240, 0, v229
	v_lshlrev_b64 v[244:245], 10, v[240:241]
	v_lshl_add_u64 v[244:245], v[62:63], 0, v[244:245]
	global_load_dwordx4 v[172:175], v[244:245], off
	s_waitcnt lgkmcnt(0)
	v_max_i32_e32 v240, 0, v230
	v_lshlrev_b64 v[246:247], 10, v[240:241]
	v_lshl_add_u64 v[246:247], v[62:63], 0, v[246:247]
	global_load_dwordx4 v[176:179], v[246:247], off
	v_max_i32_e32 v240, 0, v231
	v_lshlrev_b64 v[248:249], 10, v[240:241]
	v_lshl_add_u64 v[248:249], v[62:63], 0, v[248:249]
	global_load_dwordx4 v[180:183], v[248:249], off
	s_waitcnt lgkmcnt(3)
	s_waitcnt lgkmcnt(2)
	s_waitcnt lgkmcnt(1)
	s_waitcnt lgkmcnt(0)
	s_waitcnt lgkmcnt(0)
	s_barrier
	ds_read_b128 v[108:111], v84 offset:58880
	ds_read_b32 v58, v75 offset:57856
	s_waitcnt lgkmcnt(1)
	v_mfma_f32_16x16x32_bf16 v[108:111], v[54:57], v[108:111], 0
	ds_read_b128 v[112:115], v84 offset:58944
	ds_read_b128 v[116:119], v84 offset:59008
	s_waitcnt lgkmcnt(2)
	v_cmp_gt_i32_e32 vcc, 0, v58
	s_waitcnt lgkmcnt(1)
	v_mfma_f32_16x16x32_bf16 v[108:111], v[46:49], v[112:115], v[108:111]
	s_waitcnt lgkmcnt(0)
	v_mfma_f32_16x16x32_bf16 v[108:111], v[50:53], v[116:119], v[108:111]
	ds_read_b128 v[112:115], v84 offset:59072
	ds_read_b128 v[116:119], v84 offset:59136
	s_waitcnt lgkmcnt(1)
	v_mfma_f32_16x16x32_bf16 v[108:111], v[42:45], v[112:115], v[108:111]
	s_waitcnt lgkmcnt(0)
	v_mfma_f32_16x16x32_bf16 v[108:111], v[22:25], v[116:119], v[108:111]
	ds_read_b128 v[112:115], v84 offset:59200
	ds_read_b128 v[116:119], v84 offset:59264
	s_waitcnt lgkmcnt(1)
	v_mfma_f32_16x16x32_bf16 v[108:111], v[18:21], v[112:115], v[108:111]
	ds_read_b128 v[112:115], v84 offset:59328
	s_waitcnt lgkmcnt(1)
	v_mfma_f32_16x16x32_bf16 v[108:111], v[14:17], v[116:119], v[108:111]
	s_waitcnt lgkmcnt(0)
	v_mfma_f32_16x16x32_bf16 v[108:111], v[10:13], v[112:115], v[108:111]
	s_nop 7
	v_mul_f32_e32 v67, 0x3db504f3, v108
	v_mul_f32_e32 v108, 0x3db504f3, v109
	v_mul_f32_e32 v109, 0x3db504f3, v110
	v_mul_f32_e32 v110, 0x3db504f3, v111
	v_cndmask_b32_e32 v58, v67, v72, vcc
	v_cndmask_b32_e32 v67, v108, v72, vcc
	v_cndmask_b32_e32 v108, v109, v72, vcc
	v_cndmask_b32_e32 v109, v110, v72, vcc
	ds_write2st64_b32 v76, v58, v67 offset0:65 offset1:69
	ds_write2st64_b32 v76, v108, v109 offset0:73 offset1:77
	s_waitcnt lgkmcnt(0)
	s_barrier
	s_waitcnt vmcnt(15)
	ds_write_b128 v73, v[184:187] offset:58880
	s_waitcnt vmcnt(14)
	ds_write_b128 v74, v[188:191] offset:8448
	s_waitcnt vmcnt(13)
	ds_write_b128 v74, v[192:195] offset:16896
	s_waitcnt vmcnt(12)
	ds_write_b128 v74, v[196:199] offset:25344
	s_waitcnt vmcnt(11)
	ds_write_b128 v74, v[200:203] offset:33792
	s_waitcnt vmcnt(10)
	ds_write_b128 v74, v[204:207] offset:42240
	s_waitcnt vmcnt(9)
	ds_write_b128 v74, v[208:211] offset:50688
	s_waitcnt vmcnt(8)
	ds_write_b128 v74, v[212:215] offset:59136
	ds_read2_b32 v[224:225], v91 offset0:64 offset1:72
	ds_read2_b32 v[226:227], v91 offset0:80 offset1:88
	ds_read2_b32 v[228:229], v91 offset0:96 offset1:104
	ds_read2_b32 v[230:231], v91 offset0:112 offset1:120
	v_mov_b32_e32 v241, 0
	s_waitcnt lgkmcnt(3)
	v_max_i32_e32 v240, 0, v224
	v_lshlrev_b64 v[242:243], 10, v[240:241]
	v_lshl_add_u64 v[242:243], v[62:63], 0, v[242:243]
	global_load_dwordx4 v[184:187], v[242:243], off
	v_max_i32_e32 v240, 0, v225
	v_lshlrev_b64 v[244:245], 10, v[240:241]
	v_lshl_add_u64 v[244:245], v[62:63], 0, v[244:245]
	global_load_dwordx4 v[188:191], v[244:245], off
	s_waitcnt lgkmcnt(2)
	v_max_i32_e32 v240, 0, v226
	v_lshlrev_b64 v[246:247], 10, v[240:241]
	v_lshl_add_u64 v[246:247], v[62:63], 0, v[246:247]
	global_load_dwordx4 v[192:195], v[246:247], off
	v_max_i32_e32 v240, 0, v227
	v_lshlrev_b64 v[248:249], 10, v[240:241]
	v_lshl_add_u64 v[248:249], v[62:63], 0, v[248:249]
	global_load_dwordx4 v[196:199], v[248:249], off
	s_waitcnt lgkmcnt(1)
	v_max_i32_e32 v240, 0, v228
	v_lshlrev_b64 v[242:243], 10, v[240:241]
	v_lshl_add_u64 v[242:243], v[62:63], 0, v[242:243]
	global_load_dwordx4 v[200:203], v[242:243], off
	v_max_i32_e32 v240, 0, v229
	v_lshlrev_b64 v[244:245], 10, v[240:241]
	v_lshl_add_u64 v[244:245], v[62:63], 0, v[244:245]
	global_load_dwordx4 v[204:207], v[244:245], off
	s_waitcnt lgkmcnt(0)
	v_max_i32_e32 v240, 0, v230
	v_lshlrev_b64 v[246:247], 10, v[240:241]
	v_lshl_add_u64 v[246:247], v[62:63], 0, v[246:247]
	global_load_dwordx4 v[208:211], v[246:247], off
	v_max_i32_e32 v240, 0, v231
	v_lshlrev_b64 v[248:249], 10, v[240:241]
	v_lshl_add_u64 v[248:249], v[62:63], 0, v[248:249]
	global_load_dwordx4 v[212:215], v[248:249], off
	s_waitcnt lgkmcnt(3)
	s_waitcnt lgkmcnt(2)
	s_waitcnt lgkmcnt(1)
	s_waitcnt lgkmcnt(0)
	s_waitcnt lgkmcnt(0)
	s_barrier
	ds_read_b128 v[108:111], v84 offset:58880
	ds_read_b32 v58, v75 offset:58112
	s_waitcnt lgkmcnt(1)
	v_mfma_f32_16x16x32_bf16 v[108:111], v[54:57], v[108:111], 0
	ds_read_b128 v[112:115], v84 offset:58944
	ds_read_b128 v[116:119], v84 offset:59008
	s_waitcnt lgkmcnt(2)
	v_cmp_gt_i32_e32 vcc, 0, v58
	s_waitcnt lgkmcnt(1)
	v_mfma_f32_16x16x32_bf16 v[108:111], v[46:49], v[112:115], v[108:111]
	s_waitcnt lgkmcnt(0)
	v_mfma_f32_16x16x32_bf16 v[108:111], v[50:53], v[116:119], v[108:111]
	ds_read_b128 v[112:115], v84 offset:59072
	ds_read_b128 v[116:119], v84 offset:59136
	s_waitcnt lgkmcnt(1)
	v_mfma_f32_16x16x32_bf16 v[108:111], v[42:45], v[112:115], v[108:111]
	s_waitcnt lgkmcnt(0)
	v_mfma_f32_16x16x32_bf16 v[108:111], v[22:25], v[116:119], v[108:111]
	ds_read_b128 v[112:115], v84 offset:59200
	ds_read_b128 v[116:119], v84 offset:59264
	s_waitcnt lgkmcnt(1)
	v_mfma_f32_16x16x32_bf16 v[108:111], v[18:21], v[112:115], v[108:111]
	ds_read_b128 v[112:115], v84 offset:59328
	s_waitcnt lgkmcnt(1)
	v_mfma_f32_16x16x32_bf16 v[108:111], v[14:17], v[116:119], v[108:111]
	s_waitcnt lgkmcnt(0)
	v_mfma_f32_16x16x32_bf16 v[108:111], v[10:13], v[112:115], v[108:111]
	s_nop 7
	v_mul_f32_e32 v67, 0x3db504f3, v108
	v_mul_f32_e32 v108, 0x3db504f3, v109
	v_mul_f32_e32 v109, 0x3db504f3, v110
	v_mul_f32_e32 v110, 0x3db504f3, v111
	v_cndmask_b32_e32 v58, v67, v72, vcc
	v_cndmask_b32_e32 v67, v108, v72, vcc
	v_cndmask_b32_e32 v108, v109, v72, vcc
	v_cndmask_b32_e32 v109, v110, v72, vcc
	ds_write2st64_b32 v76, v58, v67 offset0:66 offset1:70
	ds_write2st64_b32 v76, v108, v109 offset0:74 offset1:78
	s_waitcnt lgkmcnt(0)
	s_barrier
	s_waitcnt vmcnt(15)
	ds_write_b128 v73, v[152:155] offset:58880
	s_waitcnt vmcnt(14)
	ds_write_b128 v74, v[156:159] offset:8448
	s_waitcnt vmcnt(13)
	ds_write_b128 v74, v[160:163] offset:16896
	s_waitcnt vmcnt(12)
	ds_write_b128 v74, v[164:167] offset:25344
	s_waitcnt vmcnt(11)
	ds_write_b128 v77, v[168:171]
	s_waitcnt vmcnt(10)
	ds_write_b128 v77, v[172:175] offset:8448
	s_waitcnt vmcnt(9)
	ds_write_b128 v77, v[176:179] offset:16896
	s_waitcnt vmcnt(8)
	ds_write_b128 v77, v[180:183] offset:25344
	ds_read2_b32 v[224:225], v91 offset0:0 offset1:8
	ds_read2_b32 v[226:227], v91 offset0:16 offset1:24
	v_mov_b32_e32 v241, 0
	s_waitcnt lgkmcnt(1)
	v_max_i32_e32 v240, 0, v224
	v_lshlrev_b64 v[242:243], 10, v[240:241]
	v_lshl_add_u64 v[242:243], v[62:63], 0, v[242:243]
	global_load_dwordx4 v[152:155], v[242:243], off
	v_max_i32_e32 v240, 0, v225
	v_lshlrev_b64 v[244:245], 10, v[240:241]
	v_lshl_add_u64 v[244:245], v[62:63], 0, v[244:245]
	global_load_dwordx4 v[156:159], v[244:245], off
	s_waitcnt lgkmcnt(0)
	v_max_i32_e32 v240, 0, v226
	v_lshlrev_b64 v[246:247], 10, v[240:241]
	v_lshl_add_u64 v[246:247], v[62:63], 0, v[246:247]
	global_load_dwordx4 v[160:163], v[246:247], off
	v_max_i32_e32 v240, 0, v227
	v_lshlrev_b64 v[248:249], 10, v[240:241]
	v_lshl_add_u64 v[248:249], v[62:63], 0, v[248:249]
	global_load_dwordx4 v[164:167], v[248:249], off
	s_waitcnt lgkmcnt(3)
	s_waitcnt lgkmcnt(2)
	s_waitcnt lgkmcnt(1)
	s_waitcnt lgkmcnt(0)
	s_waitcnt lgkmcnt(0)
	s_barrier
	ds_read_b128 v[108:111], v85
	ds_read_b128 v[112:115], v85 offset:64
	s_waitcnt lgkmcnt(1)
	v_mfma_f32_16x16x32_bf16 v[108:111], v[54:57], v[108:111], 0
	s_waitcnt lgkmcnt(0)
	v_mfma_f32_16x16x32_bf16 v[108:111], v[46:49], v[112:115], v[108:111]
	ds_read_b128 v[112:115], v85 offset:128
	ds_read_b128 v[116:119], v85 offset:192
	s_waitcnt lgkmcnt(1)
	v_mfma_f32_16x16x32_bf16 v[108:111], v[50:53], v[112:115], v[108:111]
	s_waitcnt lgkmcnt(0)
	v_mfma_f32_16x16x32_bf16 v[108:111], v[42:45], v[116:119], v[108:111]
	ds_read_b128 v[112:115], v85 offset:256
	ds_read_b128 v[116:119], v85 offset:320
	s_waitcnt lgkmcnt(1)
	v_mfma_f32_16x16x32_bf16 v[108:111], v[22:25], v[112:115], v[108:111]
	s_waitcnt lgkmcnt(0)
	v_mfma_f32_16x16x32_bf16 v[108:111], v[18:21], v[116:119], v[108:111]
	ds_read_b128 v[112:115], v85 offset:384
	ds_read_b128 v[116:119], v85 offset:448
	ds_read_b32 v58, v75 offset:58368
	s_waitcnt lgkmcnt(0)
	v_cmp_gt_i32_e32 vcc, 0, v58
	v_mfma_f32_16x16x32_bf16 v[108:111], v[14:17], v[112:115], v[108:111]
	v_mfma_f32_16x16x32_bf16 v[108:111], v[10:13], v[116:119], v[108:111]
	s_nop 7
	v_mul_f32_e32 v67, 0x3db504f3, v108
	v_mul_f32_e32 v108, 0x3db504f3, v109
	v_mul_f32_e32 v109, 0x3db504f3, v110
	v_mul_f32_e32 v110, 0x3db504f3, v111
	v_cndmask_b32_e32 v58, v67, v72, vcc
	v_cndmask_b32_e32 v67, v108, v72, vcc
	v_cndmask_b32_e32 v108, v109, v72, vcc
	v_cndmask_b32_e32 v109, v110, v72, vcc
	ds_write2st64_b32 v76, v58, v67 offset0:67 offset1:71
	ds_write2st64_b32 v76, v108, v109 offset0:75 offset1:79
	s_waitcnt lgkmcnt(0)
	s_barrier
	s_waitcnt vmcnt(11)
	ds_write_b128 v73, v[184:187] offset:58880
	s_waitcnt vmcnt(10)
	ds_write_b128 v74, v[188:191] offset:8448
	s_waitcnt vmcnt(9)
	ds_write_b128 v74, v[192:195] offset:16896
	s_waitcnt vmcnt(8)
	ds_write_b128 v74, v[196:199] offset:25344
	s_waitcnt vmcnt(7)
	ds_write_b128 v74, v[200:203] offset:33792
	s_waitcnt vmcnt(6)
	ds_write_b128 v74, v[204:207] offset:42240
	s_waitcnt vmcnt(5)
	ds_write_b128 v74, v[208:211] offset:50688
	s_waitcnt vmcnt(4)
	ds_write_b128 v74, v[212:215] offset:59136
	ds_read2_b32 v[224:225], v90 offset0:192 offset1:200
	ds_read2_b32 v[226:227], v90 offset0:208 offset1:216
	ds_read2_b32 v[228:229], v90 offset0:224 offset1:232
	ds_read2_b32 v[230:231], v90 offset0:240 offset1:248
	v_mov_b32_e32 v241, 0
	s_waitcnt lgkmcnt(3)
	v_max_i32_e32 v240, 0, v224
	v_lshlrev_b64 v[242:243], 10, v[240:241]
	v_lshl_add_u64 v[242:243], v[62:63], 0, v[242:243]
	global_load_dwordx4 v[184:187], v[242:243], off
	v_max_i32_e32 v240, 0, v225
	v_lshlrev_b64 v[244:245], 10, v[240:241]
	v_lshl_add_u64 v[244:245], v[62:63], 0, v[244:245]
	global_load_dwordx4 v[188:191], v[244:245], off
	s_waitcnt lgkmcnt(2)
	v_max_i32_e32 v240, 0, v226
	v_lshlrev_b64 v[246:247], 10, v[240:241]
	v_lshl_add_u64 v[246:247], v[62:63], 0, v[246:247]
	global_load_dwordx4 v[192:195], v[246:247], off
	v_max_i32_e32 v240, 0, v227
	v_lshlrev_b64 v[248:249], 10, v[240:241]
	v_lshl_add_u64 v[248:249], v[62:63], 0, v[248:249]
	global_load_dwordx4 v[196:199], v[248:249], off
	s_waitcnt lgkmcnt(1)
	v_max_i32_e32 v240, 0, v228
	v_lshlrev_b64 v[242:243], 10, v[240:241]
	v_lshl_add_u64 v[242:243], v[62:63], 0, v[242:243]
	global_load_dwordx4 v[200:203], v[242:243], off
	v_max_i32_e32 v240, 0, v229
	v_lshlrev_b64 v[244:245], 10, v[240:241]
	v_lshl_add_u64 v[244:245], v[62:63], 0, v[244:245]
	global_load_dwordx4 v[204:207], v[244:245], off
	s_waitcnt lgkmcnt(0)
	v_max_i32_e32 v240, 0, v230
	v_lshlrev_b64 v[246:247], 10, v[240:241]
	v_lshl_add_u64 v[246:247], v[62:63], 0, v[246:247]
	global_load_dwordx4 v[208:211], v[246:247], off
	v_max_i32_e32 v240, 0, v231
	v_lshlrev_b64 v[248:249], 10, v[240:241]
	v_lshl_add_u64 v[248:249], v[62:63], 0, v[248:249]
	global_load_dwordx4 v[212:215], v[248:249], off
	s_waitcnt lgkmcnt(1)
	s_waitcnt lgkmcnt(0)
	s_waitcnt lgkmcnt(0)
	s_barrier
	ds_read_b128 v[92:95], v84 offset:58880
	ds_read_b32 v58, v75 offset:58624
	s_waitcnt lgkmcnt(1)
	v_mfma_f32_16x16x32_bf16 v[54:57], v[54:57], v[92:95], 0
	ds_read_b128 v[92:95], v84 offset:58944
	ds_read_b128 v[96:99], v84 offset:59008
	s_waitcnt lgkmcnt(2)
	v_cmp_gt_i32_e32 vcc, 0, v58
	s_waitcnt lgkmcnt(1)
	v_mfma_f32_16x16x32_bf16 v[46:49], v[46:49], v[92:95], v[54:57]
	s_waitcnt lgkmcnt(0)
	v_mfma_f32_16x16x32_bf16 v[46:49], v[50:53], v[96:99], v[46:49]
	ds_read_b128 v[50:53], v84 offset:59072
	ds_read_b128 v[54:57], v84 offset:59136
	s_waitcnt lgkmcnt(1)
	v_mfma_f32_16x16x32_bf16 v[42:45], v[42:45], v[50:53], v[46:49]
	v_mov_b32_e32 v50, v59
	v_mov_b32_e32 v51, v59
	s_nop 1
	ds_read_b128 v[46:49], v84 offset:59200
	s_waitcnt lgkmcnt(1)
	v_mfma_f32_16x16x32_bf16 v[22:25], v[22:25], v[54:57], v[42:45]
	v_mov_b32_e32 v52, v59
	s_nop 1
	ds_read_b128 v[42:45], v84 offset:59264
	s_waitcnt lgkmcnt(1)
	v_mfma_f32_16x16x32_bf16 v[18:21], v[18:21], v[46:49], v[22:25]
	v_mov_b32_e32 v47, v59
	v_mov_b32_e32 v46, v59
	s_nop 0
	ds_read_b128 v[22:25], v84 offset:59328
	s_waitcnt lgkmcnt(1)
	v_mfma_f32_16x16x32_bf16 v[14:17], v[14:17], v[42:45], v[18:21]
	v_mov_b32_e32 v42, v59
	v_mov_b32_e32 v43, v59
	v_mov_b32_e32 v44, v59
	s_waitcnt lgkmcnt(0)
	v_mfma_f32_16x16x32_bf16 v[10:13], v[10:13], v[22:25], v[14:17]
	s_nop 7
	v_mul_f32_e32 v10, 0x3db504f3, v10
	v_mul_f32_e32 v11, 0x3db504f3, v11
	v_mul_f32_e32 v12, 0x3db504f3, v12
	v_mul_f32_e32 v13, 0x3db504f3, v13
	v_cndmask_b32_e32 v10, v10, v72, vcc
	v_cndmask_b32_e32 v11, v11, v72, vcc
	v_cndmask_b32_e32 v12, v12, v72, vcc
	v_cndmask_b32_e32 v13, v13, v72, vcc
	ds_write2st64_b32 v76, v10, v11 offset0:68 offset1:72
	ds_write2st64_b32 v76, v12, v13 offset0:76 offset1:80
	s_waitcnt lgkmcnt(0)
	s_barrier
	ds_read2st64_b32 v[10:11], v78 offset0:65 offset1:66
	ds_read2st64_b32 v[12:13], v78 offset0:129 offset1:130
	ds_read2st64_b32 v[14:15], v78 offset0:131 offset1:132
	ds_read2st64_b32 v[16:17], v78 offset0:67 offset1:68
	ds_read2st64_b32 v[18:19], v79 offset0:65 offset1:66
	ds_read2st64_b32 v[20:21], v79 offset0:129 offset1:130
	ds_read2st64_b32 v[22:23], v79 offset0:131 offset1:132
	ds_read2st64_b32 v[24:25], v79 offset0:67 offset1:68
	s_waitcnt lgkmcnt(6)
	v_add_f32_e32 v10, v10, v12
	v_add_f32_e32 v11, v11, v13
	s_waitcnt lgkmcnt(4)
	v_add_f32_e32 v12, v16, v14
	v_add_f32_e32 v13, v17, v15
	s_waitcnt lgkmcnt(2)
	v_add_f32_e32 v14, v18, v20
	v_add_f32_e32 v15, v19, v21
	v_max3_f32 v18, v10, s17, v11
	s_waitcnt lgkmcnt(0)
	v_add_f32_e32 v16, v24, v22
	v_add_f32_e32 v17, v25, v23
	v_max3_f32 v19, v14, s17, v15
	v_max3_f32 v18, v18, v12, v13
	v_max3_f32 v19, v19, v16, v17
	s_nop 0
	v_mov_b32_dpp v50, v18 quad_perm:[1,0,3,2] row_mask:0xf bank_mask:0xf
	v_mov_b32_dpp v47, v19 quad_perm:[1,0,3,2] row_mask:0xf bank_mask:0xf
	v_max_f32_e32 v20, v50, v50
	v_max_f32_e32 v21, v47, v47
	v_max_f32_e32 v18, v18, v20
	v_max_f32_e32 v19, v19, v21
	s_nop 0
	v_mov_b32_dpp v51, v18 quad_perm:[2,3,0,1] row_mask:0xf bank_mask:0xf
	v_mov_b32_dpp v42, v19 quad_perm:[2,3,0,1] row_mask:0xf bank_mask:0xf
	v_max_f32_e32 v20, v51, v51
	v_max_f32_e32 v21, v42, v42
	v_max_f32_e32 v18, v18, v20
	v_max_f32_e32 v19, v19, v21
	s_nop 0
	v_mov_b32_dpp v52, v18 row_half_mirror row_mask:0xf bank_mask:0xf
	v_mov_b32_dpp v43, v19 row_half_mirror row_mask:0xf bank_mask:0xf
	v_max_f32_e32 v20, v52, v52
	v_max_f32_e32 v21, v43, v43
	v_max_f32_e32 v18, v18, v20
	v_max_f32_e32 v19, v19, v21
	s_nop 0
	v_mov_b32_dpp v46, v18 row_mirror row_mask:0xf bank_mask:0xf
	v_mov_b32_dpp v44, v19 row_mirror row_mask:0xf bank_mask:0xf
	v_max_f32_e32 v20, v46, v46
	v_max_f32_e32 v21, v44, v44
	v_max_f32_e32 v18, v18, v20
	v_max_f32_e32 v19, v19, v21
	v_readlane_b32 s11, v18, 32
	v_readlane_b32 s12, v18, 48
	v_readlane_b32 s7, v18, 0
	v_readlane_b32 s10, v18, 16
	v_readlane_b32 s13, v19, 0
	v_readlane_b32 s18, v19, 16
	v_readlane_b32 s19, v19, 32
	v_readlane_b32 s20, v19, 48
	v_max_f32_e64 v18, s12, s12
	v_max_f32_e64 v19, s11, s11
	v_mov_b32_e32 v20, s10
	v_max_f32_e64 v21, s20, s20
	v_max_f32_e64 v22, s19, s19
	v_max_f32_e32 v18, v19, v18
	v_mov_b32_e32 v23, s18
	v_max_f32_e32 v19, v22, v21
	v_max3_f32 v18, s7, v20, v18
	v_max3_f32 v19, s13, v23, v19
	v_sub_f32_e32 v10, v10, v18
	v_sub_f32_e32 v11, v11, v18
	v_sub_f32_e32 v14, v14, v19
	v_mul_f32_e32 v10, 0x3fb8aa3b, v10
	v_sub_f32_e32 v12, v12, v18
	v_sub_f32_e32 v15, v15, v19
	v_mul_f32_e32 v11, 0x3fb8aa3b, v11
	v_mul_f32_e32 v14, 0x3fb8aa3b, v14
	v_exp_f32_e32 v10, v10
	v_sub_f32_e32 v13, v13, v18
	v_sub_f32_e32 v16, v16, v19
	v_mul_f32_e32 v12, 0x3fb8aa3b, v12
	v_mul_f32_e32 v15, 0x3fb8aa3b, v15
	v_exp_f32_e32 v11, v11
	v_exp_f32_e32 v14, v14
	v_sub_f32_e32 v17, v17, v19
	v_mul_f32_e32 v13, 0x3fb8aa3b, v13
	v_mul_f32_e32 v16, 0x3fb8aa3b, v16
	v_exp_f32_e32 v12, v12
	v_exp_f32_e32 v15, v15
	v_mul_f32_e32 v17, 0x3fb8aa3b, v17
	v_exp_f32_e32 v13, v13
	v_exp_f32_e32 v16, v16
	v_exp_f32_e32 v17, v17
	v_add_f32_e32 v18, 0, v10
	v_add_f32_e32 v19, 0, v14
	v_add_f32_e32 v18, v11, v18
	v_add_f32_e32 v19, v15, v19
	v_add_f32_e32 v18, v12, v18
	v_add_f32_e32 v19, v16, v19
	v_add_f32_e32 v18, v13, v18
	v_add_f32_e32 v19, v17, v19
	s_nop 0
	v_add_f32_dpp v18, v18, v18 quad_perm:[1,0,3,2] row_mask:0xf bank_mask:0xf bound_ctrl:1
	v_add_f32_dpp v19, v19, v19 quad_perm:[1,0,3,2] row_mask:0xf bank_mask:0xf bound_ctrl:1
	s_nop 0
	v_add_f32_dpp v18, v18, v18 quad_perm:[2,3,0,1] row_mask:0xf bank_mask:0xf bound_ctrl:1
	v_add_f32_dpp v19, v19, v19 quad_perm:[2,3,0,1] row_mask:0xf bank_mask:0xf bound_ctrl:1
	s_nop 0
	v_add_f32_dpp v18, v18, v18 row_half_mirror row_mask:0xf bank_mask:0xf bound_ctrl:1
	v_add_f32_dpp v19, v19, v19 row_half_mirror row_mask:0xf bank_mask:0xf bound_ctrl:1
	s_nop 0
	v_add_f32_dpp v18, v18, v18 row_mirror row_mask:0xf bank_mask:0xf bound_ctrl:1
	v_add_f32_dpp v19, v19, v19 row_mirror row_mask:0xf bank_mask:0xf bound_ctrl:1
	v_readlane_b32 s10, v18, 16
	v_readlane_b32 s12, v18, 48
	v_readlane_b32 s7, v18, 0
	v_readlane_b32 s11, v18, 32
	v_readlane_b32 s13, v19, 0
	v_readlane_b32 s18, v19, 16
	v_readlane_b32 s19, v19, 32
	v_readlane_b32 s20, v19, 48
	v_mov_b32_e32 v18, s10
	v_mov_b32_e32 v19, s12
	v_add_f32_e32 v18, s7, v18
	v_add_f32_e32 v19, s11, v19
	v_add_f32_e32 v18, v18, v19
	v_div_scale_f32 v19, s[10:11], v18, v18, 1.0
	v_rcp_f32_e32 v22, v19
	v_div_scale_f32 v23, vcc, 1.0, v18, 1.0
	v_mov_b32_e32 v20, s18
	v_fma_f32 v24, -v19, v22, 1.0
	v_fmac_f32_e32 v22, v24, v22
	v_mul_f32_e32 v24, v23, v22
	v_fma_f32 v25, -v19, v24, v23
	v_fmac_f32_e32 v24, v25, v22
	v_fma_f32 v19, -v19, v24, v23
	v_div_fmas_f32 v19, v19, v22, v24
	v_div_fixup_f32 v18, v19, v18, 1.0
	v_mul_f32_e32 v10, v10, v18
	v_mul_f32_e32 v11, v11, v18
	v_mul_f32_e32 v12, v12, v18
	v_mul_f32_e32 v13, v13, v18
	v_bfe_u32 v18, v10, 16, 1
	v_mov_b32_e32 v21, s20
	v_bfe_u32 v19, v11, 16, 1
	v_bfe_u32 v22, v12, 16, 1
	v_add3_u32 v10, v10, v18, s9
	v_add_f32_e32 v20, s13, v20
	v_add3_u32 v11, v11, v19, s9
	v_add3_u32 v12, v12, v22, s9
	ds_write_b16_d16_hi v86, v10 offset:49408
	ds_write_b16_d16_hi v86, v11 offset:49536
	ds_write_b16_d16_hi v86, v12 offset:49664
	v_add_f32_e32 v10, s19, v21
	v_add_f32_e32 v10, v20, v10
	v_div_scale_f32 v11, s[10:11], v10, v10, 1.0
	v_rcp_f32_e32 v12, v11
	v_bfe_u32 v18, v13, 16, 1
	v_add3_u32 v13, v13, v18, s9
	ds_write_b16_d16_hi v86, v13 offset:49792
	v_fma_f32 v13, -v11, v12, 1.0
	v_fmac_f32_e32 v12, v13, v12
	v_div_scale_f32 v13, vcc, 1.0, v10, 1.0
	v_mul_f32_e32 v18, v13, v12
	v_fma_f32 v19, -v11, v18, v13
	v_fmac_f32_e32 v18, v19, v12
	v_fma_f32 v11, -v11, v18, v13
	v_div_fmas_f32 v11, v11, v12, v18
	v_div_fixup_f32 v10, v11, v10, 1.0
	v_mul_f32_e32 v11, v14, v10
	v_bfe_u32 v12, v11, 16, 1
	v_add3_u32 v11, v11, v12, s9
	ds_write_b16_d16_hi v87, v11 offset:49408
	v_mul_f32_e32 v11, v15, v10
	v_bfe_u32 v12, v11, 16, 1
	v_add3_u32 v11, v11, v12, s9
	ds_write_b16_d16_hi v87, v11 offset:49536
	v_mul_f32_e32 v11, v16, v10
	v_bfe_u32 v12, v11, 16, 1
	v_add3_u32 v11, v11, v12, s9
	v_mul_f32_e32 v10, v17, v10
	ds_write_b16_d16_hi v87, v11 offset:49664
	v_bfe_u32 v11, v10, 16, 1
	s_cselect_b64 s[10:11], -1, 0
	v_add3_u32 v10, v10, v11, s9
	s_and_b64 vcc, exec, s[10:11]
	ds_write_b16_d16_hi v87, v10 offset:49792
	s_cbranch_vccnz .LBB0_1399
	s_ashr_i32 s7, s6, 31
	s_lshl_b64 s[12:13], s[6:7], 14
	s_add_u32 s12, s14, s12
	s_addc_u32 s13, s15, s13
	v_mov_b32_e32 v67, v59
	v_lshl_add_u64 v[2:3], s[12:13], 0, v[66:67]
	v_add_co_u32_e32 v10, vcc, 0x2000, v2
	s_nop 1
	v_addc_co_u32_e32 v11, vcc, 0, v3, vcc
	global_load_dwordx4 v[2:5], v66, s[12:13]
	global_load_dwordx4 v[6:9], v[10:11], off
	s_and_saveexec_b64 s[12:13], s[4:5]
	s_cbranch_execz .LBB0_1398
	s_lshl_b64 s[18:19], s[6:7], 10
	v_lshl_add_u64 v[10:11], v[60:61], 0, s[18:19]
	global_load_dword v1, v[10:11], off
	s_branch .LBB0_1398
